# retention: k-chunk permutation of the Q/K/state b128 LDS fragment reads (same on both MFMA operands) makes them bank-conflict-free with the existing 528-byte row stride
# speedup vs baseline: 1.0059x; 1.0059x over previous
; DI void phase_retention(const Params& p, LAS unsigned char* lds, int cblk) {
;     const int tid = threadIdx.x, lane = tid & 63, w = tid >> 6, fr = lane & 15, fq = lane >> 4;
;     LAS unsigned char* Qs = lds; LAS unsigned char* Ks = lds + 33792; LAS unsigned char* Vs = lds + 67584; LAS unsigned char* St = lds + 76800; LAS unsigned char* Ps = lds + 110592;
;     LAS float* red = (LAS float*)(lds + 119808);
;     const bf16_t* rq = (const bf16_t*)(p.ws + WS_RQ); const bf16_t* rk = (const bf16_t*)(p.ws + WS_RK); bf16_t* rv = (bf16_t*)p.out; float* retss = (float*)(p.ws + WS_RETSS);
;     for (int item = cblk; item < 256; item += gridDim.x) {
;         const int q5 = item >> 3, bh = (item & 7) * 4 + (q5 & 3), slice = q5 >> 2, b = bh >> 3, h = bh & 7;
;         const float lg = log1pf(-exp2f(-5.0f - (float)h));
;         const float gamma_c = expf(64.0f * lg);
;         const float xv = expf(-lg * (float)((tid >> 3) + 1));
;         const float xo0 = expf(lg * (float)(32 * (w & 1) + fr + 1)), xo1 = expf(lg * (float)(32 * (w & 1) + 16 + fr + 1));
;         const size_t tok0 = (size_t)b * SEQ;
;         const bf16_t* qbase = rq + tok0 * 2048 + h * 256 + (tid & 31) * 8; const bf16_t* kbase = rk + tok0 * 2048 + h * 256 + (tid & 31) * 8;
;         bf16_t* vbase = rv + tok0 * 4096 + h * 512 + slice * 64;
;         u32x4 pq[4], pk[4], pv;
;         f32x4 Sreg[2][4];
; #pragma unroll
;         for (int a = 0; a < 2; ++a)
; #pragma unroll
;             for (int bb = 0; bb < 4; ++bb) Sreg[a][bb] = (f32x4){0.f, 0.f, 0.f, 0.f};
;         for (int i = tid; i < 33792 / 16; i += 512) ((LAS u32x4*)St)[i] = (u32x4){0u, 0u, 0u, 0u};
;     ...
;         RET_LOAD(0); RET_STORE();
;         __syncthreads();
;     ...
;                     const bf16x8 kf = *(const LAS bf16x8*)(Ks + (16 * jt + fr) * 528 + (32 * ks + 8 * fq) * 2);
; #pragma unroll
;                     for (int t = 0; t < 2; ++t) { qfr[ks][t] = *(const LAS bf16x8*)(Qs + (16 * (it0 + t) + fr) * 528 + (32 * ks + 8 * fq) * 2); sa[t] = mfma16(kf, qfr[ks][t], sa[t]); }
;                 }
; #pragma unroll
;                 for (int t = 0; t < 2; ++t) { const int iq = 16 * (it0 + t) + fr, jk0 = 16 * jt + 4 * fq;
;                     u32x2 o; o.x = cvt_pk_bf16(jk0 + 0 <= iq ? sa[t][0] : 0.f, jk0 + 1 <= iq ? sa[t][1] : 0.f); o.y = cvt_pk_bf16(jk0 + 2 <= iq ? sa[t][2] : 0.f, jk0 + 3 <= iq ? sa[t][3] : 0.f);
.LBB0_200:
	s_andn2_b64 vcc, exec, s[0:1]
	v_bfe_u32 v137, v74, 2, 2
	v_and_b32_e32 v136, 15, v74
	v_lshlrev_b32_e32 v138, 3, v74
	v_lshlrev_b32_e32 v139, 4, v74
	v_cmp_gt_u32_e64 s[0:1], 64, v74
	s_cbranch_vccnz .LBB0_220
	s_add_u32 s40, s30, 0x14e00000
	s_addc_u32 s41, s31, 0
	s_add_u32 s42, s30, 0x1ce00000
	s_addc_u32 s43, s31, 0
	s_add_u32 s44, s30, 0x400000
	s_addc_u32 s45, s31, 0
	s_add_i32 s2, 0, 0x10800
	v_lshrrev_b32_e32 v2, 3, v74
	s_movk_i32 s4, 0x90
	v_mov_b32_e32 v10, s2
	v_lshrrev_b32_e32 v14, 7, v74
	v_and_b32_e32 v18, 24, v138
	v_mad_u32_u24 v13, v2, s4, v10
	v_lshlrev_b32_e32 v10, 4, v14
	v_and_b32_e32 v16, 0x3c0, v74
	v_add_u32_e32 v145, s2, v18
	s_add_i32 s2, 0, 0x12c00
	v_or_b32_e32 v15, v10, v136
	s_movk_i32 s4, 0x210
	v_add3_u32 v32, 0, v16, v18
	v_mov_b32_e32 v18, s2
	v_mad_u32_u24 v17, v15, s4, 0
	v_mad_u32_u24 v15, v15, s4, v18
	v_mbcnt_lo_u32_b32 v18, -1, 0
	v_mbcnt_hi_u32_b32 v18, -1, v18
	v_and_b32_e32 v22, 64, v18
	v_xor_b32_e32 v20, 16, v18
	v_add_u32_e32 v22, 64, v22
	v_cmp_lt_i32_e32 vcc, v20, v22
	v_bfe_u32 v3, v74, 4, 2
	v_lshlrev_b32_e32 v144, 6, v74
	v_cndmask_b32_e32 v20, v18, v20, vcc
	v_lshlrev_b32_e32 v19, 4, v3
	v_lshlrev_b32_e32 v12, 2, v3
	v_lshlrev_b32_e32 v27, 3, v3
	v_lshlrev_b32_e32 v147, 2, v20
	v_xor_b32_e32 v20, 32, v18
	v_cmp_eq_u32_e64 s[20:21], 0, v3
	v_add_u32_e32 v3, 0x8000, v144
	v_cmp_lt_i32_e32 vcc, v20, v22
	v_add3_u32 v33, s2, v16, v27
	v_and_b32_e32 v16, 0x1f800, v3
	v_add_u32_e32 v3, 0x18000, v144
	v_cndmask_b32_e32 v18, v18, v20, vcc
	v_and_b32_e32 v20, 0x3f800, v3
	v_add_u32_e32 v3, 0x200, v74
	v_add_u32_e32 v4, 1, v2
	v_lshrrev_b32_e32 v3, 5, v3
	v_cvt_f32_u32_e32 v141, v4
	v_lshrrev_b32_e32 v4, 1, v74
	v_mul_u32_u24_e32 v35, 0x210, v3
	v_add_u32_e32 v3, 0x600, v74
	v_and_or_b32 v5, v4, 32, v136
	v_or_b32_e32 v21, v12, v10
	v_lshrrev_b32_e32 v3, 5, v3
	v_or_b32_e32 v23, 2, v21
	v_mul_u32_u24_e32 v36, 0x210, v3
	v_or_b32_e32 v3, 16, v5
	v_or_b32_e32 v24, 3, v21
	s_add_i32 s22, 0, 0x1b000
	v_or_b32_e32 v26, v27, v137
	s_add_i32 s4, 0, 0x1d400
	v_cmp_gt_u32_e64 s[8:9], v23, v5
	v_cmp_gt_u32_e64 s[16:17], v23, v3
	v_or_b32_e32 v23, 32, v27
	v_mov_b32_e32 v77, 0
	v_lshl_add_u32 v25, v21, 1, s22
	v_lshlrev_b32_e32 v28, 5, v14
	v_lshl_add_u32 v149, v14, 2, s4
	v_cmp_gt_u32_e64 s[4:5], v21, v5
	v_cmp_lt_u32_e64 s[6:7], v21, v5
	v_cmp_gt_u32_e64 s[10:11], v24, v5
	v_cmp_gt_u32_e64 s[12:13], v21, v3
	v_cmp_lt_u32_e64 s[14:15], v21, v3
	v_cmp_gt_u32_e64 s[18:19], v24, v3
	v_mul_u32_u24_e32 v21, 0x210, v26
	v_mul_u32_u24_e32 v150, 0x90, v26
	v_or_b32_e32 v24, v23, v137
	v_lshl_add_u32 v42, v23, 1, s22
	v_lshlrev_b32_e32 v26, 12, v3
	v_lshlrev_b32_e32 v152, 4, v3
	v_add_u32_e32 v154, s2, v139
	v_lshlrev_b32_e32 v3, 12, v74
	v_lshlrev_b32_e32 v23, 13, v136
	s_mov_b32 s2, 0x40000
	v_and_b32_e32 v7, 7, v74
	v_add_u32_e32 v146, v145, v28
	v_or_b32_e32 v76, v28, v27
	v_and_or_b32 v28, v3, s2, v23
	v_mov_b32_e32 v3, v77
	v_lshlrev_b32_e32 v6, 12, v2
	v_lshlrev_b32_e32 v8, 3, v7
	v_lshlrev_b32_e32 v7, 4, v7
	v_lshlrev_b64 v[2:3], 13, v[2:3]
	v_or_b32_e32 v2, v2, v7
	v_add_u32_e32 v40, s22, v19
	v_mov_b32_e32 v75, v77
	v_mov_b32_e32 v29, v77
	v_lshl_add_u64 v[2:3], s[28:29], 0, v[2:3]
	s_mov_b64 s[22:23], 0x80000
	v_or_b32_e32 v30, 0x20000, v28
	v_lshl_add_u64 v[28:29], v[76:77], 0, v[28:29]
	v_lshl_add_u64 v[82:83], v[2:3], 0, s[22:23]
	v_lshlrev_b64 v[2:3], 7, v[74:75]
	s_mov_b64 s[22:23], 0x30000
	v_lshl_add_u64 v[80:81], s[28:29], 0, v[28:29]
	v_lshl_add_u64 v[28:29], v[2:3], 0, s[22:23]
	v_add_u32_e32 v4, 1, v5
	v_and_b32_e32 v9, 0x1f0, v139
	v_and_b32_e32 v23, 0xfffff000, v28
	s_mov_b64 s[22:23], 0x10000
	v_cvt_f32_ubyte0_e32 v142, v4
	v_add_u32_e32 v4, 17, v5
	v_and_b32_e32 v14, 0xf800, v144
	v_lshrrev_b32_e32 v22, 5, v74
	v_mov_b32_e32 v31, v77
	v_or_b32_e32 v84, v23, v9
	v_mov_b32_e32 v23, v77
	v_lshl_add_u64 v[2:3], v[2:3], 0, s[22:23]
	v_cvt_f32_ubyte0_e32 v143, v4
	v_and_b32_e32 v4, 0xf8, v138
	v_add_u32_e32 v11, 0, v9
	v_lshlrev_b32_e32 v148, 2, v18
	v_or_b32_e32 v18, 0x10000, v14
	v_mul_u32_u24_e32 v34, 0x210, v22
	v_mul_u32_u24_e32 v37, 0x210, v5
	v_add_u32_e32 v38, 0, v19
	v_mul_u32_u24_e32 v39, 0x90, v5
	v_mul_u32_u24_e32 v41, 0x90, v24
	v_lshlrev_b32_e32 v24, 12, v5
	v_lshlrev_b32_e32 v151, 4, v5
	v_mul_u32_u24_e32 v5, 0x210, v136
	v_lshl_add_u64 v[30:31], v[76:77], 0, v[30:31]
	v_lshlrev_b64 v[86:87], 12, v[22:23]
	v_and_b32_e32 v2, 0xfffff000, v2
	s_mov_b32 s3, 0
	v_add_u32_e32 v153, 0xfffffe00, v74
	s_lshl_b32 s46, s81, 12
	s_lshl_b32 s47, s33, 12
	s_lshl_b32 s48, s81, 2
	s_lshl_b32 s49, s33, 2
	v_lshl_add_u64 v[78:79], s[28:29], 0, v[30:31]
	v_and_b32_e32 v85, 0xff, v29
	v_or_b32_e32 v86, v86, v9
	v_and_b32_e32 v89, 0xff, v3
	v_or_b32_e32 v88, v2, v9
	s_movk_i32 s50, 0x63f
	s_mov_b32 s51, 0xc2fc0000
	s_mov_b32 s52, 0x3f2aaaab
	v_mov_b32_e32 v75, 0x3ecc95a3
	s_mov_b32 s53, 0x3f317218
	s_mov_b32 s54, 0x33800000
	s_mov_b32 s55, 0x3fb8aa3b
	s_mov_b32 s56, 0xc2ce8ed0
	s_mov_b32 s57, 0x42b17218
	v_lshlrev_b32_e32 v90, 1, v4
	v_lshlrev_b32_e32 v92, 1, v14
	v_lshlrev_b32_e32 v94, 1, v16
	v_lshlrev_b32_e32 v96, 1, v18
	v_lshlrev_b32_e32 v98, 1, v20
	v_lshlrev_b32_e32 v100, 1, v6
	v_lshlrev_b32_e32 v102, 1, v8
	s_mov_b32 s58, 0x14e40000
	s_mov_b32 s59, 0x1ce40000
	s_mov_b32 s60, 0x14e60000
	s_mov_b32 s61, 0x1ce60000
	s_mov_b32 s62, 0x5040100
	s_mov_b64 s[22:23], 0x4000
	s_mov_b64 s[24:25], 0x40000
	s_mov_b32 s63, 0x3f80000
	v_lshlrev_b32_e32 v104, 1, v10
	v_lshlrev_b32_e32 v106, 1, v12
	v_lshlrev_b32_e32 v108, 1, v24
	v_lshlrev_b32_e32 v76, 1, v26
	v_mov_b32_e32 v172, v77
	v_mov_b32_e32 v173, v77
	v_mov_b32_e32 v174, v77
	v_mov_b32_e32 v175, v77
	v_mov_b32_e32 v155, 0x42800000
	v_mov_b32_e32 v156, 0x7fc00000
	v_mov_b32_e32 v157, 0xff800000
	v_mov_b32_e32 v158, 0x7f800000
	v_add_u32_e32 v159, v11, v34
	v_add_u32_e32 v160, v11, v35
	v_add_u32_e32 v161, v11, v36
	v_add_u32_e32 v162, v13, v7
	v_add_u32_e32 v163, v17, v19
	v_add_u32_e32 v164, v38, v37
	v_add_u32_e32 v165, v25, v39
	v_add_u32_e32 v166, v32, v21
	v_add_u32_e32 v167, v15, v19
	v_bfe_u32 v250, v74, 4, 2
	v_lshrrev_b32_e32 v251, 1, v250
	v_and_b32_e32 v252, 1, v250
	v_lshlrev_b32_e32 v251, 4, v251
	v_lshl_add_u32 v251, v252, 8, v251
	v_lshlrev_b32_e32 v250, 4, v250
	v_sub_u32_e32 v251, v251, v250
	v_add_u32_e32 v163, v163, v251
	v_add_u32_e32 v164, v164, v251
	v_add_u32_e32 v167, v167, v251
	v_add_u32_e32 v168, v40, v39
	v_add_u32_e32 v169, v146, v41
	v_add_u32_e32 v170, v42, v39
	v_add_u32_e32 v171, v33, v5
	s_mov_b32 s64, s81
	s_branch .LBB0_203

; #define LAS __attribute__((address_space(3)))
; DI f32x4 mfma16(bf16x8 a, bf16x8 b, f32x4 c) { return __builtin_amdgcn_mfma_f32_16x16x32_bf16(a, b, c, 0, 0, 0); }
; DI void phase_retention(const Params& p, LAS unsigned char* lds, int cblk) {
;     ...
;             if (c + 1 < 128) RET_LOAD(c + 1);
;             bf16x8 qfr[8][2];
;             {
;                 const int jt = w >> 1, it0 = (w & 1) * 2;
;                 f32x4 sa[2] = {(f32x4){0.f, 0.f, 0.f, 0.f}, (f32x4){0.f, 0.f, 0.f, 0.f}};
; #pragma unroll
;                 for (int ks = 0; ks < 8; ++ks) {
;                     const bf16x8 kf = *(const LAS bf16x8*)(Ks + (16 * jt + fr) * 528 + (32 * ks + 8 * fq) * 2);
; #pragma unroll
;                     for (int t = 0; t < 2; ++t) { qfr[ks][t] = *(const LAS bf16x8*)(Qs + (16 * (it0 + t) + fr) * 528 + (32 * ks + 8 * fq) * 2); sa[t] = mfma16(kf, qfr[ks][t], sa[t]); }
;                 }
; #pragma unroll
;                 for (int t = 0; t < 2; ++t) { const int iq = 16 * (it0 + t) + fr, jk0 = 16 * jt + 4 * fq;
;                     u32x2 o; o.x = cvt_pk_bf16(jk0 + 0 <= iq ? sa[t][0] : 0.f, jk0 + 1 <= iq ? sa[t][1] : 0.f); o.y = cvt_pk_bf16(jk0 + 2 <= iq ? sa[t][2] : 0.f, jk0 + 3 <= iq ? sa[t][3] : 0.f);
;                     *(LAS u32x2*)(Ps + iq * 144 + jk0 * 2) = o; }
;             }
;             {
; #pragma unroll
;                 for (int ks = 0; ks < 2; ++ks) {
;                     const int j0 = 32 * ks + 8 * fq + (fr >> 2);
;                     bf16x8 kt[2], vf[4];
; #pragma unroll
;                     for (int dd = 0; dd < 2; ++dd) { LAS unsigned char* a0 = Ks + j0 * 528 + (16 * (2 * w + dd) + 4 * (fr & 3)) * 2; kt[dd] = tr_read2(a0, a0 + 4 * 528); }
; #pragma unroll
;                     for (int vt = 0; vt < 4; ++vt) { LAS unsigned char* a0 = Vs + j0 * 144 + (16 * vt + 4 * (fr & 3)) * 2; vf[vt] = tr_read2(a0, a0 + 4 * 144); }
; #pragma unroll
;                     for (int dd = 0; dd < 2; ++dd)
; #pragma unroll
;                         for (int vt = 0; vt < 4; ++vt) Sreg[dd][vt] = mfma16(kt[dd], vf[vt], Sreg[dd][vt]);
;                 }
; #pragma unroll
;                 for (int dd = 0; dd < 2; ++dd)
; #pragma unroll
;                     for (int vt = 0; vt < 4; ++vt) Sreg[dd][vt] *= gamma_c;
;             }
;             __syncthreads();
.LBB0_207:
	ds_read_b128 v[34:37], v163 offset:33792
	ds_read_b128 v[70:73], v164
	ds_read_b128 v[38:41], v163 offset:33824
	ds_read_b128 v[176:179], v164 offset:32
	ds_read_b128 v[180:183], v164 offset:8448
	ds_read_b128 v[184:187], v164 offset:8480
	ds_read_b128 v[46:49], v163 offset:33856
	s_waitcnt lgkmcnt(5)
	v_mfma_f32_16x16x32_bf16 v[42:45], v[34:37], v[70:73], 0
	v_add_u32_e32 v93, v145, v150
	v_lshl_add_u64 v[58:59], s[30:31], 0, v[124:125]
	v_add_u32_e32 v95, v146, v150
	s_waitcnt lgkmcnt(2)
	v_mfma_f32_16x16x32_bf16 v[34:37], v[34:37], v[180:183], 0
	v_mfma_f32_16x16x32_bf16 v[42:45], v[38:41], v[176:179], v[42:45]
	s_waitcnt lgkmcnt(1)
	v_mfma_f32_16x16x32_bf16 v[34:37], v[38:41], v[184:187], v[34:37]
	ds_read_b128 v[188:191], v164 offset:64
	ds_read_b128 v[38:41], v163 offset:33888
	ds_read_b128 v[192:195], v164 offset:96
	ds_read_b128 v[196:199], v164 offset:8512
	ds_read_b128 v[200:203], v164 offset:8544
	s_waitcnt lgkmcnt(4)
	v_mfma_f32_16x16x32_bf16 v[42:45], v[46:49], v[188:191], v[42:45]
	s_waitcnt lgkmcnt(1)
	v_mfma_f32_16x16x32_bf16 v[34:37], v[46:49], v[196:199], v[34:37]
	ds_read_b128 v[46:49], v163 offset:33920
	ds_read_b128 v[50:53], v163 offset:33952
	ds_read_b128 v[204:207], v164 offset:128
	ds_read_b128 v[208:211], v164 offset:160
	v_mfma_f32_16x16x32_bf16 v[42:45], v[38:41], v[192:195], v[42:45]
	s_waitcnt lgkmcnt(4)
	v_mfma_f32_16x16x32_bf16 v[34:37], v[38:41], v[200:203], v[34:37]
	s_waitcnt lgkmcnt(1)
	v_mfma_f32_16x16x32_bf16 v[38:41], v[46:49], v[204:207], v[42:45]
	s_nop 3
	ds_read_b128 v[42:45], v163 offset:33984
	ds_read_b128 v[54:57], v163 offset:34016
	ds_read_b128 v[212:215], v164 offset:192
	ds_read_b128 v[216:219], v164 offset:224
	ds_read_b128 v[220:223], v164 offset:8576
	ds_read_b128 v[224:227], v164 offset:8608
	s_waitcnt lgkmcnt(1)
	v_mfma_f32_16x16x32_bf16 v[34:37], v[46:49], v[220:223], v[34:37]
	ds_read_b128 v[228:231], v164 offset:8640
	ds_read_b128 v[232:235], v164 offset:8672
	v_mfma_f32_16x16x32_bf16 v[38:41], v[50:53], v[208:211], v[38:41]
	s_waitcnt lgkmcnt(2)
	v_mfma_f32_16x16x32_bf16 v[34:37], v[50:53], v[224:227], v[34:37]
	v_mfma_f32_16x16x32_bf16 v[38:41], v[42:45], v[212:215], v[38:41]
	s_waitcnt lgkmcnt(1)
	v_mfma_f32_16x16x32_bf16 v[34:37], v[42:45], v[228:231], v[34:37]
	v_mfma_f32_16x16x32_bf16 v[38:41], v[54:57], v[216:219], v[38:41]
	s_waitcnt lgkmcnt(0)
	v_mfma_f32_16x16x32_bf16 v[34:37], v[54:57], v[232:235], v[34:37]
	s_nop 5
	v_cvt_pk_bf16_f32 v38, v38, s0
	v_cvt_pk_bf16_f32 v39, v39, s0
	v_cvt_pk_bf16_f32 v34, v34, s0
	v_cvt_pk_bf16_f32 v35, v35, s0
	v_cndmask_b32_e64 v38, v38, 0, s[4:5]
	v_cndmask_b32_e64 v39, 0, v39, s[6:7]
	v_cndmask_b32_e64 v34, v34, 0, s[12:13]
	v_cndmask_b32_e64 v35, 0, v35, s[14:15]
	v_perm_b32 v38, v39, v38, s62
	v_cvt_pk_bf16_f32 v39, v40, s0
	v_cvt_pk_bf16_f32 v40, v41, s0
	v_perm_b32 v34, v35, v34, s62
	v_cvt_pk_bf16_f32 v35, v36, s0
	v_cvt_pk_bf16_f32 v36, v37, s0
	v_cndmask_b32_e64 v39, v39, 0, s[8:9]
	v_cndmask_b32_e64 v40, v40, 0, s[10:11]
	v_cndmask_b32_e64 v35, v35, 0, s[16:17]
	v_cndmask_b32_e64 v36, v36, 0, s[18:19]
	v_perm_b32 v39, v40, v39, s62
	v_perm_b32 v35, v36, v35, s62
	ds_write_b64 v165, v[38:39]
	ds_write_b64 v165, v[34:35] offset:2304
	ds_read_b64_tr_b16 v[36:37], v166 offset:35904
	ds_read_b64_tr_b16 v[34:35], v166 offset:33792
	ds_read_b64_tr_b16 v[44:45], v166 offset:35936
	ds_read_b64_tr_b16 v[42:43], v166 offset:33824
	ds_read_b64_tr_b16 v[40:41], v93 offset:576
	ds_read_b64_tr_b16 v[38:39], v93
	ds_read_b64_tr_b16 v[46:47], v93 offset:32
	ds_read_b64_tr_b16 v[50:51], v93 offset:64
	ds_read_b64_tr_b16 v[54:55], v93 offset:96
	ds_read_b64_tr_b16 v[48:49], v93 offset:608
	ds_read_b64_tr_b16 v[52:53], v93 offset:640
	ds_read_b64_tr_b16 v[56:57], v93 offset:672
	s_waitcnt lgkmcnt(6)
	v_mfma_f32_16x16x32_bf16 v[6:9], v[34:37], v[38:41], v[6:9]
	s_waitcnt lgkmcnt(2)
	v_mfma_f32_16x16x32_bf16 v[10:13], v[34:37], v[46:49], v[10:13]
	s_waitcnt lgkmcnt(1)
	v_mfma_f32_16x16x32_bf16 v[18:21], v[34:37], v[50:53], v[18:21]
	s_waitcnt lgkmcnt(0)
	v_mfma_f32_16x16x32_bf16 v[30:33], v[34:37], v[54:57], v[30:33]
	v_add_co_u32_e32 v34, vcc, s58, v58
	s_nop 1
	v_addc_co_u32_e32 v35, vcc, 0, v59, vcc
	v_mfma_f32_16x16x32_bf16 v[26:29], v[42:45], v[38:41], v[26:29]
	v_add_co_u32_e32 v38, vcc, s59, v58
	s_nop 1
	v_addc_co_u32_e32 v39, vcc, 0, v59, vcc
	v_mfma_f32_16x16x32_bf16 v[22:25], v[42:45], v[46:49], v[22:25]
	v_lshl_add_u64 v[46:47], s[30:31], 0, v[126:127]
	v_add_co_u32_e32 v48, vcc, s58, v46
	global_load_dwordx4 v[34:37], v[34:35], off
	s_nop 0
	global_load_dwordx4 v[38:41], v[38:39], off
	v_addc_co_u32_e32 v49, vcc, 0, v47, vcc
	v_mfma_f32_16x16x32_bf16 v[14:17], v[42:45], v[50:53], v[14:17]
	v_add_co_u32_e32 v50, vcc, s59, v46
	v_mfma_f32_16x16x32_bf16 v[2:5], v[42:45], v[54:57], v[2:5]
	ds_read_b64_tr_b16 v[42:43], v166 offset:50688
	ds_read_b64_tr_b16 v[44:45], v166 offset:52800
	ds_read_b64_tr_b16 v[238:239], v166 offset:52832
	ds_read_b64_tr_b16 v[236:237], v166 offset:50720
	ds_read_b64_tr_b16 v[64:65], v93 offset:5184
	ds_read_b64_tr_b16 v[62:63], v93 offset:4608
	ds_read_b64_tr_b16 v[66:67], v93 offset:4640
	ds_read_b64_tr_b16 v[240:241], v93 offset:4672
	ds_read_b64_tr_b16 v[244:245], v93 offset:4704
	ds_read_b64_tr_b16 v[68:69], v93 offset:5216
	ds_read_b64_tr_b16 v[242:243], v93 offset:5248
	ds_read_b64_tr_b16 v[246:247], v93 offset:5280
	v_addc_co_u32_e32 v51, vcc, 0, v47, vcc
	v_add_co_u32_e32 v54, vcc, s60, v58
	s_waitcnt lgkmcnt(6)
	v_mfma_f32_16x16x32_bf16 v[6:9], v[42:45], v[62:65], v[6:9]
	v_addc_co_u32_e32 v55, vcc, 0, v59, vcc
	v_add_co_u32_e32 v58, vcc, s61, v58
	s_waitcnt lgkmcnt(2)
	v_mfma_f32_16x16x32_bf16 v[10:13], v[42:45], v[66:69], v[10:13]
	v_addc_co_u32_e32 v59, vcc, 0, v59, vcc
	global_load_dwordx4 v[46:49], v[48:49], off
	s_nop 0
	global_load_dwordx4 v[50:53], v[50:51], off
	s_waitcnt lgkmcnt(1)
	v_mfma_f32_16x16x32_bf16 v[18:21], v[42:45], v[240:243], v[18:21]
	global_load_dwordx4 v[54:57], v[54:55], off
	s_nop 0
	global_load_dwordx4 v[58:61], v[58:59], off
	s_waitcnt lgkmcnt(0)
	v_mfma_f32_16x16x32_bf16 v[30:33], v[42:45], v[244:247], v[30:33]
	v_lshl_add_u64 v[42:43], s[30:31], 0, v[114:115]
	v_add_co_u32_e32 v44, vcc, s58, v42
	v_mfma_f32_16x16x32_bf16 v[26:29], v[236:239], v[62:65], v[26:29]
	s_nop 0
	v_addc_co_u32_e32 v45, vcc, 0, v43, vcc
	v_add_co_u32_e32 v42, vcc, s59, v42
	v_mfma_f32_16x16x32_bf16 v[22:25], v[236:239], v[66:69], v[22:25]
	s_nop 0
	v_addc_co_u32_e32 v43, vcc, 0, v43, vcc
	global_load_dwordx4 v[62:65], v[44:45], off
	global_load_dwordx4 v[66:69], v[42:43], off
	v_lshl_add_u64 v[42:43], v[134:135], 0, s[36:37]
	global_load_dwordx4 v[42:45], v[42:43], off
	v_mfma_f32_16x16x32_bf16 v[14:17], v[236:239], v[240:243], v[14:17]
	s_barrier
; #define LAS __attribute__((address_space(3)))
; DI f32x4 mfma16(bf16x8 a, bf16x8 b, f32x4 c) { return __builtin_amdgcn_mfma_f32_16x16x32_bf16(a, b, c, 0, 0, 0); }
; DI bf16x8 tr_read2(LAS unsigned char* p0, LAS unsigned char* p1) { s16x4 lo = tr_read(p0), hi = tr_read(p1); return __builtin_shufflevector(lo, hi, 0, 1, 2, 3, 4, 5, 6, 7); }
; DI void phase_retention(const Params& p, LAS unsigned char* lds, int cblk) {
;     ...
;             {
;                 const int vt = w >> 1, it0 = (w & 1) * 2;
;                 f32x4 oa[2] = {(f32x4){0.f, 0.f, 0.f, 0.f}, (f32x4){0.f, 0.f, 0.f, 0.f}};
; #pragma unroll
;                 for (int ks = 0; ks < 8; ++ks) {
;                     const bf16x8 sf = *(const LAS bf16x8*)(St + (16 * vt + fr) * 528 + (32 * ks + 8 * fq) * 2);
; #pragma unroll
;                     for (int t = 0; t < 2; ++t) oa[t] = mfma16(sf, qfr[ks][t], oa[t]);
;                 }
; #pragma unroll
;                 for (int ks = 0; ks < 2; ++ks) {
;                     const int j0 = 32 * ks + 8 * fq + (fr >> 2);
;                     LAS unsigned char* a0 = Vs + j0 * 144 + (16 * vt + 4 * (fr & 3)) * 2; const bf16x8 vf = tr_read2(a0, a0 + 4 * 144);
; #pragma unroll
;                     for (int t = 0; t < 2; ++t) { const bf16x8 pf = *(const LAS bf16x8*)(Ps + (16 * (it0 + t) + fr) * 144 + (32 * ks + 8 * fq) * 2); oa[t] = mfma16(vf, pf, oa[t]); }
;                 }
; #pragma unroll
;                 for (int t = 0; t < 2; ++t) { const int iq = 16 * (it0 + t) + fr; oa[t] *= (t == 0 ? xo0 : xo1);
;                     u32x2 o; o.x = cvt_pk_bf16(oa[t][0], oa[t][1]); o.y = cvt_pk_bf16(oa[t][2], oa[t][3]);
;                     *(u32x2*)(vbase + (size_t)(64 * c + iq) * 4096 + 16 * vt + 4 * fq) = o;
;                     float ss = (oa[t][0] * oa[t][0] + oa[t][1] * oa[t][1]) + (oa[t][2] * oa[t][2] + oa[t][3] * oa[t][3]);
;                     ss += __shfl_xor(ss, 16); ss += __shfl_xor(ss, 32);
;                     if (fq == 0) red[iq * 4 + vt] = ss; }
	v_mfma_f32_16x16x32_bf16 v[2:5], v[236:239], v[244:247], v[2:5]
	ds_read_b128 v[236:239], v167
	ds_read_b128 v[240:243], v167 offset:32
	s_waitcnt lgkmcnt(1)
	v_mfma_f32_16x16x32_bf16 v[70:73], v[236:239], v[70:73], 0
	v_mfma_f32_16x16x32_bf16 v[180:183], v[236:239], v[180:183], 0
	s_waitcnt lgkmcnt(0)
	v_mfma_f32_16x16x32_bf16 v[70:73], v[240:243], v[176:179], v[70:73]
	v_mfma_f32_16x16x32_bf16 v[176:179], v[240:243], v[184:187], v[180:183]
	s_nop 4
	ds_read_b128 v[180:183], v167 offset:64
	ds_read_b128 v[184:187], v167 offset:96
	s_waitcnt lgkmcnt(1)
	v_mfma_f32_16x16x32_bf16 v[70:73], v[180:183], v[188:191], v[70:73]
	v_mfma_f32_16x16x32_bf16 v[176:179], v[180:183], v[196:199], v[176:179]
	s_waitcnt lgkmcnt(0)
	v_mfma_f32_16x16x32_bf16 v[70:73], v[184:187], v[192:195], v[70:73]
	v_mfma_f32_16x16x32_bf16 v[176:179], v[184:187], v[200:203], v[176:179]
	ds_read_b128 v[180:183], v167 offset:128
	ds_read_b128 v[184:187], v167 offset:160
	ds_read_b128 v[188:191], v167 offset:224
	s_waitcnt lgkmcnt(2)
	v_mfma_f32_16x16x32_bf16 v[70:73], v[180:183], v[204:207], v[70:73]
	v_mfma_f32_16x16x32_bf16 v[176:179], v[180:183], v[220:223], v[176:179]
	ds_read_b128 v[180:183], v167 offset:192
	ds_read_b64_tr_b16 v[192:193], v95
	ds_read_b64_tr_b16 v[194:195], v95 offset:576
	ds_read_b128 v[196:199], v168
	ds_read_b64_tr_b16 v[200:201], v169
	ds_read_b64_tr_b16 v[202:203], v169 offset:576
	ds_read_b128 v[204:207], v168 offset:2304
	s_waitcnt lgkmcnt(8)
	v_mfma_f32_16x16x32_bf16 v[70:73], v[184:187], v[208:211], v[70:73]
	s_waitcnt lgkmcnt(6)
	v_mfma_f32_16x16x32_bf16 v[70:73], v[180:183], v[212:215], v[70:73]
	v_mfma_f32_16x16x32_bf16 v[70:73], v[188:191], v[216:219], v[70:73]
	s_waitcnt lgkmcnt(3)
	v_mfma_f32_16x16x32_bf16 v[70:73], v[192:195], v[196:199], v[70:73]
	ds_read_b128 v[196:199], v170
	ds_read_b128 v[208:211], v170 offset:2304
	s_waitcnt lgkmcnt(1)
	v_mfma_f32_16x16x32_bf16 v[70:73], v[200:203], v[196:199], v[70:73]
	v_mfma_f32_16x16x32_bf16 v[176:179], v[184:187], v[224:227], v[176:179]
	s_nop 6
	v_mul_f32_e64 v196, v122, v72
	v_mul_f32_e64 v197, v123, v73
	v_pk_mul_f32 v[184:185], v[118:119], v[70:71]
	v_mul_f32_e32 v99, v196, v196
	v_mfma_f32_16x16x32_bf16 v[70:73], v[180:183], v[228:231], v[176:179]
	v_mul_f32_e32 v97, v185, v185
	v_fmac_f32_e32 v97, v184, v184
	v_fmac_f32_e32 v99, v197, v197
	v_mfma_f32_16x16x32_bf16 v[70:73], v[188:191], v[232:235], v[70:73]
	v_add_f32_e32 v97, v97, v99
	ds_bpermute_b32 v99, v147, v97
	v_cvt_pk_bf16_f32 v186, v184, v185
	v_mfma_f32_16x16x32_bf16 v[70:73], v[192:195], v[204:207], v[70:73]
	v_cvt_pk_bf16_f32 v187, v196, v197
	v_lshl_add_u64 v[176:177], v[132:133], 0, s[36:37]
	s_waitcnt lgkmcnt(0)
	v_add_f32_e32 v97, v97, v99
	ds_bpermute_b32 v99, v148, v97
	v_mfma_f32_16x16x32_bf16 v[70:73], v[200:203], v[208:211], v[70:73]
	global_store_dwordx2 v[176:177], v[186:187], off
	s_and_saveexec_b64 s[38:39], s[20:21]
	s_cbranch_execz .LBB0_209
	s_waitcnt lgkmcnt(0)
	v_add_f32_e32 v97, v97, v99
	v_add_u32_e32 v99, v149, v151
	ds_write_b32 v99, v97

; #define LAS __attribute__((address_space(3)))
; DI f32x4 mfma16(bf16x8 a, bf16x8 b, f32x4 c) { return __builtin_amdgcn_mfma_f32_16x16x32_bf16(a, b, c, 0, 0, 0); }
; DI void phase_retention(const Params& p, LAS unsigned char* lds, int cblk) {
;     ...
;             bf16x8 qfr[8][2];
;             {
;                 const int jt = w >> 1, it0 = (w & 1) * 2;
;                 f32x4 sa[2] = {(f32x4){0.f, 0.f, 0.f, 0.f}, (f32x4){0.f, 0.f, 0.f, 0.f}};
; #pragma unroll
;                 for (int ks = 0; ks < 8; ++ks) {
;                     const bf16x8 kf = *(const LAS bf16x8*)(Ks + (16 * jt + fr) * 528 + (32 * ks + 8 * fq) * 2);
; #pragma unroll
;                     for (int t = 0; t < 2; ++t) { qfr[ks][t] = *(const LAS bf16x8*)(Qs + (16 * (it0 + t) + fr) * 528 + (32 * ks + 8 * fq) * 2); sa[t] = mfma16(kf, qfr[ks][t], sa[t]); }
;                 }
; #pragma unroll
;                 for (int t = 0; t < 2; ++t) { const int iq = 16 * (it0 + t) + fr, jk0 = 16 * jt + 4 * fq;
;                     u32x2 o; o.x = cvt_pk_bf16(jk0 + 0 <= iq ? sa[t][0] : 0.f, jk0 + 1 <= iq ? sa[t][1] : 0.f); o.y = cvt_pk_bf16(jk0 + 2 <= iq ? sa[t][2] : 0.f, jk0 + 3 <= iq ? sa[t][3] : 0.f);
;                     *(LAS u32x2*)(Ps + iq * 144 + jk0 * 2) = o; }
;             }
;             {
; #pragma unroll
;                 for (int ks = 0; ks < 2; ++ks) {
;                     const int j0 = 32 * ks + 8 * fq + (fr >> 2);
;                     bf16x8 kt[2], vf[4];
; #pragma unroll
;                     for (int dd = 0; dd < 2; ++dd) { LAS unsigned char* a0 = Ks + j0 * 528 + (16 * (2 * w + dd) + 4 * (fr & 3)) * 2; kt[dd] = tr_read2(a0, a0 + 4 * 528); }
; #pragma unroll
;                     for (int vt = 0; vt < 4; ++vt) { LAS unsigned char* a0 = Vs + j0 * 144 + (16 * vt + 4 * (fr & 3)) * 2; vf[vt] = tr_read2(a0, a0 + 4 * 144); }
; #pragma unroll
;                     for (int dd = 0; dd < 2; ++dd)
; #pragma unroll
;                         for (int vt = 0; vt < 4; ++vt) Sreg[dd][vt] = mfma16(kt[dd], vf[vt], Sreg[dd][vt]);
;                 }
; #pragma unroll
;                 for (int dd = 0; dd < 2; ++dd)
; #pragma unroll
;                     for (int vt = 0; vt < 4; ++vt) Sreg[dd][vt] *= gamma_c;
;             }
;             __syncthreads();
.LBB0_213:
	ds_read_b128 v[34:37], v163 offset:33792
	ds_read_b128 v[38:41], v164
	ds_read_b128 v[42:45], v163 offset:33824
	ds_read_b128 v[46:49], v164 offset:32
	ds_read_b128 v[54:57], v164 offset:8448
	ds_read_b128 v[58:61], v164 offset:8480
	ds_read_b128 v[62:65], v163 offset:33856
	s_waitcnt lgkmcnt(5)
	v_mfma_f32_16x16x32_bf16 v[50:53], v[34:37], v[38:41], 0
	v_mov_b32_e32 v105, v77
	v_lshl_add_u64 v[114:115], s[34:35], 0, v[104:105]
	v_mov_b32_e32 v107, v77
	s_waitcnt lgkmcnt(2)
	v_mfma_f32_16x16x32_bf16 v[34:37], v[34:37], v[54:57], 0
	v_mov_b32_e32 v109, v77
	v_mfma_f32_16x16x32_bf16 v[50:53], v[42:45], v[46:49], v[50:53]
	s_waitcnt lgkmcnt(1)
	v_mfma_f32_16x16x32_bf16 v[34:37], v[42:45], v[58:61], v[34:37]
	ds_read_b128 v[42:45], v164 offset:64
	ds_read_b128 v[66:69], v163 offset:33888
	ds_read_b128 v[124:127], v164 offset:96
	ds_read_b128 v[128:131], v164 offset:8512
	ds_read_b128 v[132:135], v164 offset:8544
	s_waitcnt lgkmcnt(4)
	v_mfma_f32_16x16x32_bf16 v[50:53], v[62:65], v[42:45], v[50:53]
	s_waitcnt lgkmcnt(1)
	v_mfma_f32_16x16x32_bf16 v[34:37], v[62:65], v[128:131], v[34:37]
	ds_read_b128 v[62:65], v163 offset:33920
	v_mfma_f32_16x16x32_bf16 v[50:53], v[66:69], v[124:127], v[50:53]
	s_waitcnt lgkmcnt(1)
	v_mfma_f32_16x16x32_bf16 v[34:37], v[66:69], v[132:135], v[34:37]
	ds_read_b128 v[66:69], v164 offset:128
	ds_read_b128 v[176:179], v163 offset:33952
	ds_read_b128 v[180:183], v164 offset:160
	ds_read_b128 v[184:187], v164 offset:8576
	ds_read_b128 v[188:191], v164 offset:8608
	s_waitcnt lgkmcnt(4)
	v_mfma_f32_16x16x32_bf16 v[50:53], v[62:65], v[66:69], v[50:53]
	s_waitcnt lgkmcnt(1)
	v_mfma_f32_16x16x32_bf16 v[34:37], v[62:65], v[184:187], v[34:37]
	ds_read_b128 v[62:65], v163 offset:33984
	v_mfma_f32_16x16x32_bf16 v[50:53], v[176:179], v[180:183], v[50:53]
	s_waitcnt lgkmcnt(1)
	v_mfma_f32_16x16x32_bf16 v[34:37], v[176:179], v[188:191], v[34:37]
	ds_read_b128 v[176:179], v164 offset:192
	ds_read_b128 v[192:195], v163 offset:34016
	ds_read_b128 v[196:199], v164 offset:224
	ds_read_b128 v[200:203], v164 offset:8640
	ds_read_b128 v[204:207], v164 offset:8672
	s_waitcnt lgkmcnt(4)
	v_mfma_f32_16x16x32_bf16 v[50:53], v[62:65], v[176:179], v[50:53]
	s_waitcnt lgkmcnt(1)
	v_mfma_f32_16x16x32_bf16 v[34:37], v[62:65], v[200:203], v[34:37]
	v_mfma_f32_16x16x32_bf16 v[50:53], v[192:195], v[196:199], v[50:53]
	s_waitcnt lgkmcnt(0)
	v_mfma_f32_16x16x32_bf16 v[34:37], v[192:195], v[204:207], v[34:37]
	s_nop 5
	v_cvt_pk_bf16_f32 v50, v50, s0
	v_cvt_pk_bf16_f32 v51, v51, s0
	v_cvt_pk_bf16_f32 v34, v34, s0
	v_cvt_pk_bf16_f32 v35, v35, s0
	v_cndmask_b32_e64 v50, v50, 0, s[4:5]
	v_cndmask_b32_e64 v51, 0, v51, s[6:7]
	v_cndmask_b32_e64 v34, v34, 0, s[12:13]
	v_cndmask_b32_e64 v35, 0, v35, s[14:15]
	v_perm_b32 v50, v51, v50, s62
	v_cvt_pk_bf16_f32 v51, v52, s0
	v_cvt_pk_bf16_f32 v52, v53, s0
	v_perm_b32 v34, v35, v34, s62
	v_cvt_pk_bf16_f32 v35, v36, s0
	v_cvt_pk_bf16_f32 v36, v37, s0
	v_cndmask_b32_e64 v51, v51, 0, s[8:9]
	v_cndmask_b32_e64 v52, v52, 0, s[10:11]
	v_cndmask_b32_e64 v35, v35, 0, s[16:17]
	v_cndmask_b32_e64 v36, v36, 0, s[18:19]
	v_perm_b32 v51, v52, v51, s62
	v_perm_b32 v35, v36, v35, s62
	ds_write_b64 v165, v[50:51]
	ds_write_b64 v165, v[34:35] offset:2304
	ds_read_b64_tr_b16 v[36:37], v166 offset:35904
	ds_read_b64_tr_b16 v[34:35], v166 offset:33792
	ds_read_b64_tr_b16 v[52:53], v166 offset:35936
	ds_read_b64_tr_b16 v[50:51], v166 offset:33824
	ds_read_b64_tr_b16 v[64:65], v93 offset:576
	ds_read_b64_tr_b16 v[62:63], v93
	ds_read_b64_tr_b16 v[192:193], v93 offset:32
	ds_read_b64_tr_b16 v[208:209], v93 offset:64
	ds_read_b64_tr_b16 v[212:213], v93 offset:96
	ds_read_b64_tr_b16 v[194:195], v93 offset:608
	ds_read_b64_tr_b16 v[210:211], v93 offset:640
	ds_read_b64_tr_b16 v[214:215], v93 offset:672
	s_waitcnt lgkmcnt(6)
	v_mfma_f32_16x16x32_bf16 v[6:9], v[34:37], v[62:65], v[6:9]
	s_waitcnt lgkmcnt(2)
	v_mfma_f32_16x16x32_bf16 v[10:13], v[34:37], v[192:195], v[10:13]
	s_waitcnt lgkmcnt(1)
	v_mfma_f32_16x16x32_bf16 v[18:21], v[34:37], v[208:211], v[18:21]
	s_waitcnt lgkmcnt(0)
	v_mfma_f32_16x16x32_bf16 v[34:37], v[34:37], v[212:215], v[30:33]
	v_mfma_f32_16x16x32_bf16 v[62:65], v[50:53], v[62:65], v[26:29]
	v_mfma_f32_16x16x32_bf16 v[192:195], v[50:53], v[192:195], v[22:25]
	v_mfma_f32_16x16x32_bf16 v[208:211], v[50:53], v[208:211], v[14:17]
	v_mfma_f32_16x16x32_bf16 v[2:5], v[50:53], v[212:215], v[2:5]
	s_nop 1
	ds_read_b64_tr_b16 v[14:15], v166 offset:50688
	ds_read_b64_tr_b16 v[16:17], v166 offset:52800
	ds_read_b64_tr_b16 v[52:53], v166 offset:52832
	ds_read_b64_tr_b16 v[50:51], v166 offset:50720
	ds_read_b64_tr_b16 v[214:215], v93 offset:5184
	ds_read_b64_tr_b16 v[212:213], v93 offset:4608
	ds_read_b64_tr_b16 v[216:217], v93 offset:4640
	ds_read_b64_tr_b16 v[220:221], v93 offset:4672
	ds_read_b64_tr_b16 v[224:225], v93 offset:4704
	ds_read_b64_tr_b16 v[218:219], v93 offset:5216
	ds_read_b64_tr_b16 v[222:223], v93 offset:5248
	ds_read_b64_tr_b16 v[226:227], v93 offset:5280
	s_waitcnt lgkmcnt(0)
	s_barrier
; #define LAS __attribute__((address_space(3)))
; DI f32x4 mfma16(bf16x8 a, bf16x8 b, f32x4 c) { return __builtin_amdgcn_mfma_f32_16x16x32_bf16(a, b, c, 0, 0, 0); }
; DI bf16x8 tr_read2(LAS unsigned char* p0, LAS unsigned char* p1) { s16x4 lo = tr_read(p0), hi = tr_read(p1); return __builtin_shufflevector(lo, hi, 0, 1, 2, 3, 4, 5, 6, 7); }
; DI void phase_retention(const Params& p, LAS unsigned char* lds, int cblk) {
;     ...
;             {
;                 const int vt = w >> 1, it0 = (w & 1) * 2;
;                 f32x4 oa[2] = {(f32x4){0.f, 0.f, 0.f, 0.f}, (f32x4){0.f, 0.f, 0.f, 0.f}};
; #pragma unroll
;                 for (int ks = 0; ks < 8; ++ks) {
;                     const bf16x8 sf = *(const LAS bf16x8*)(St + (16 * vt + fr) * 528 + (32 * ks + 8 * fq) * 2);
; #pragma unroll
;                     for (int t = 0; t < 2; ++t) oa[t] = mfma16(sf, qfr[ks][t], oa[t]);
;                 }
; #pragma unroll
;                 for (int ks = 0; ks < 2; ++ks) {
;                     const int j0 = 32 * ks + 8 * fq + (fr >> 2);
;                     LAS unsigned char* a0 = Vs + j0 * 144 + (16 * vt + 4 * (fr & 3)) * 2; const bf16x8 vf = tr_read2(a0, a0 + 4 * 144);
; #pragma unroll
;                     for (int t = 0; t < 2; ++t) { const bf16x8 pf = *(const LAS bf16x8*)(Ps + (16 * (it0 + t) + fr) * 144 + (32 * ks + 8 * fq) * 2); oa[t] = mfma16(vf, pf, oa[t]); }
;                 }
; #pragma unroll
;                 for (int t = 0; t < 2; ++t) { const int iq = 16 * (it0 + t) + fr; oa[t] *= (t == 0 ? xo0 : xo1);
;                     u32x2 o; o.x = cvt_pk_bf16(oa[t][0], oa[t][1]); o.y = cvt_pk_bf16(oa[t][2], oa[t][3]);
;                     *(u32x2*)(vbase + (size_t)(64 * c + iq) * 4096 + 16 * vt + 4 * fq) = o;
;                     float ss = (oa[t][0] * oa[t][0] + oa[t][1] * oa[t][1]) + (oa[t][2] * oa[t][2] + oa[t][3] * oa[t][3]);
;                     ss += __shfl_xor(ss, 16); ss += __shfl_xor(ss, 32);
;                     if (fq == 0) red[iq * 4 + vt] = ss; }
	v_mfma_f32_16x16x32_bf16 v[30:33], v[14:17], v[212:215], v[6:9]
	v_mfma_f32_16x16x32_bf16 v[26:29], v[14:17], v[216:219], v[10:13]
	v_mfma_f32_16x16x32_bf16 v[22:25], v[14:17], v[220:223], v[18:21]
	v_mfma_f32_16x16x32_bf16 v[18:21], v[14:17], v[224:227], v[34:37]
	v_mfma_f32_16x16x32_bf16 v[14:17], v[50:53], v[212:215], v[62:65]
	v_mfma_f32_16x16x32_bf16 v[10:13], v[50:53], v[216:219], v[192:195]
	v_mfma_f32_16x16x32_bf16 v[6:9], v[50:53], v[220:223], v[208:211]
	v_mfma_f32_16x16x32_bf16 v[2:5], v[50:53], v[224:227], v[2:5]
	ds_read_b128 v[34:37], v167
	ds_read_b128 v[50:53], v167 offset:32
	s_waitcnt lgkmcnt(1)
	v_mfma_f32_16x16x32_bf16 v[38:41], v[34:37], v[38:41], 0
	v_mfma_f32_16x16x32_bf16 v[34:37], v[34:37], v[54:57], 0
	s_waitcnt lgkmcnt(0)
	v_mfma_f32_16x16x32_bf16 v[38:41], v[50:53], v[46:49], v[38:41]
	v_mfma_f32_16x16x32_bf16 v[34:37], v[50:53], v[58:61], v[34:37]
	ds_read_b128 v[46:49], v167 offset:64
	ds_read_b128 v[50:53], v167 offset:96
	s_waitcnt lgkmcnt(1)
	v_mfma_f32_16x16x32_bf16 v[38:41], v[46:49], v[42:45], v[38:41]
	ds_read_b128 v[42:45], v167 offset:128
	v_mfma_f32_16x16x32_bf16 v[34:37], v[46:49], v[128:131], v[34:37]
	ds_read_b128 v[46:49], v167 offset:160
	s_waitcnt lgkmcnt(2)
	v_mfma_f32_16x16x32_bf16 v[38:41], v[50:53], v[124:127], v[38:41]
	v_mfma_f32_16x16x32_bf16 v[34:37], v[50:53], v[132:135], v[34:37]
	ds_read_b128 v[50:53], v167 offset:192
	ds_read_b128 v[54:57], v167 offset:224
	ds_read_b64_tr_b16 v[58:59], v95
	ds_read_b64_tr_b16 v[60:61], v95 offset:576
	s_waitcnt lgkmcnt(5)
	v_mfma_f32_16x16x32_bf16 v[38:41], v[42:45], v[66:69], v[38:41]
	ds_read_b128 v[62:65], v168
	ds_read_b64_tr_b16 v[66:67], v169
	ds_read_b64_tr_b16 v[68:69], v169 offset:576
	ds_read_b128 v[124:127], v168 offset:2304
	ds_read_b128 v[128:131], v170
	s_waitcnt lgkmcnt(9)
	v_mfma_f32_16x16x32_bf16 v[38:41], v[46:49], v[180:183], v[38:41]
	s_waitcnt lgkmcnt(8)
	v_mfma_f32_16x16x32_bf16 v[38:41], v[50:53], v[176:179], v[38:41]
	s_waitcnt lgkmcnt(7)
	v_mfma_f32_16x16x32_bf16 v[38:41], v[54:57], v[196:199], v[38:41]
	v_mfma_f32_16x16x32_bf16 v[34:37], v[42:45], v[184:187], v[34:37]
	s_waitcnt lgkmcnt(4)
	v_mfma_f32_16x16x32_bf16 v[38:41], v[58:61], v[62:65], v[38:41]
	ds_read_b128 v[62:65], v170 offset:2304
	v_mfma_f32_16x16x32_bf16 v[34:37], v[46:49], v[188:191], v[34:37]
	s_waitcnt lgkmcnt(1)
	v_mfma_f32_16x16x32_bf16 v[128:131], v[66:69], v[128:131], v[38:41]
	v_mfma_f32_16x16x32_bf16 v[34:37], v[50:53], v[200:203], v[34:37]
	s_nop 2
	v_lshl_add_u64 v[38:39], v[114:115], 0, v[106:107]
	s_nop 2
	v_pk_mul_f32 v[40:41], v[122:123], v[130:131]
	v_pk_mul_f32 v[114:115], v[118:119], v[128:129]
	v_cvt_pk_bf16_f32 v43, v40, v41
	v_mul_f32_e32 v46, v115, v115
	v_mul_f32_e32 v40, v40, v40
	v_fmac_f32_e32 v46, v114, v114
	v_fmac_f32_e32 v40, v41, v41
	v_mfma_f32_16x16x32_bf16 v[34:37], v[54:57], v[204:207], v[34:37]
	v_add_f32_e32 v40, v46, v40
	ds_bpermute_b32 v41, v147, v40
	v_lshl_add_u64 v[44:45], v[38:39], 0, v[108:109]
	v_mfma_f32_16x16x32_bf16 v[34:37], v[58:61], v[124:127], v[34:37]
	v_add_co_u32_e32 v44, vcc, s63, v44
	s_waitcnt lgkmcnt(0)
	v_add_f32_e32 v40, v40, v41
	ds_bpermute_b32 v41, v148, v40
	v_mfma_f32_16x16x32_bf16 v[34:37], v[66:69], v[62:65], v[34:37]
	v_cvt_pk_bf16_f32 v42, v114, v115
	v_addc_co_u32_e32 v45, vcc, 0, v45, vcc
	global_store_dwordx2 v[44:45], v[42:43], off
	s_and_saveexec_b64 s[34:35], s[20:21]
	s_cbranch_execz .LBB0_215
	s_waitcnt lgkmcnt(0)
	v_add_f32_e32 v40, v40, v41
	v_add_u32_e32 v41, v149, v151
	ds_write_b32 v41, v40
